# attention tile head: all K/V fragment reads issued first, the next tile's six LDS-DMA loads issued under the first six K.Q^T MFMAs
# speedup vs baseline: 1.0100x; 1.0022x over previous
.Latt_loop:
	s_waitcnt vmcnt(0)
	s_barrier
	ds_read_b128 v[64:67], v173 offset:24576
	ds_read_b128 v[68:71], v173 offset:28672
	ds_read_b128 v[72:75], v171 offset:24576
	ds_read_b128 v[76:79], v171 offset:28672
	ds_read_b128 v[216:219], v169 offset:24576
	ds_read_b128 v[220:223], v169 offset:28672
	ds_read_b128 v[224:227], v167 offset:24576
	ds_read_b128 v[228:231], v167 offset:28672
	ds_read_b128 v[232:235], v173 offset:32768
	ds_read_b128 v[236:239], v173 offset:36864
	ds_read_b128 v[240:243], v173 offset:40960
	ds_read_b128 v[244:247], v173 offset:45056
	s_mov_b32 m0, s44
	s_waitcnt lgkmcnt(11)
	v_mfma_f32_32x32x16_bf16 v[112:127], v[64:67], v[140:143], v[96:111]
	ds_read_b128 v[64:67], v171 offset:32768
	global_load_lds_dwordx4 v200, s[40:41]
	s_add_u32 m0, s44, 0x400
	s_waitcnt lgkmcnt(11)
	v_mfma_f32_32x32x16_bf16 v[80:95], v[68:71], v[140:143], v[96:111]
	ds_read_b128 v[68:71], v171 offset:36864
	global_load_lds_dwordx4 v190, s[40:41]
	s_mov_b32 m0, s45
	s_waitcnt lgkmcnt(11)
	v_mfma_f32_32x32x16_bf16 v[112:127], v[72:75], v[136:139], v[112:127]
	ds_read_b128 v[72:75], v171 offset:40960
	global_load_lds_dwordx4 v192, s[42:43]
	s_add_u32 m0, s45, 0x400
	s_waitcnt lgkmcnt(11)
	v_mfma_f32_32x32x16_bf16 v[80:95], v[76:79], v[136:139], v[80:95]
	ds_read_b128 v[76:79], v171 offset:45056
	global_load_lds_dwordx4 v194, s[42:43]
	s_add_u32 m0, s45, 0x800
	s_waitcnt lgkmcnt(11)
	v_mfma_f32_32x32x16_bf16 v[112:127], v[216:219], v[132:135], v[112:127]
	ds_read_b128 v[216:219], v169 offset:32768
	global_load_lds_dwordx4 v196, s[42:43]
	s_add_u32 m0, s45, 0xc00
	s_waitcnt lgkmcnt(11)
	v_mfma_f32_32x32x16_bf16 v[80:95], v[220:223], v[132:135], v[80:95]
	ds_read_b128 v[220:223], v169 offset:36864
	global_load_lds_dwordx4 v198, s[42:43]
	s_waitcnt lgkmcnt(11)
	v_mfma_f32_32x32x16_bf16 v[112:127], v[224:227], v[128:131], v[112:127]
	ds_read_b128 v[224:227], v169 offset:40960
	s_waitcnt lgkmcnt(11)
	v_mfma_f32_32x32x16_bf16 v[80:95], v[228:231], v[128:131], v[80:95]
	ds_read_b128 v[228:231], v169 offset:45056
	s_add_u32 s40, s40, 0x18000
	s_addc_u32 s41, s41, 0
	s_add_u32 s42, s42, 0x80
	s_addc_u32 s43, s43, 0
	s_nop 7
	s_nop 3
	v_max3_f32 v175, v112, v113, v114
	v_max3_f32 v177, v115, v116, v117
	v_max3_f32 v179, v118, v119, v120
	v_max3_f32 v181, v121, v122, v123
	v_max3_f32 v248, v124, v125, v126
	v_max3_f32 v249, v127, v80, v81
	v_max3_f32 v250, v82, v83, v84
	v_max3_f32 v251, v85, v86, v87
	v_max3_f32 v253, v88, v89, v90
	v_max3_f32 v254, v91, v92, v93
	v_max3_f32 v175, v175, v177, v179
	v_max3_f32 v181, v181, v248, v249
	v_max3_f32 v250, v250, v251, v253
	v_max3_f32 v254, v254, v94, v95
	v_max3_f32 v175, v175, v181, v250
	v_max_f32_e32 v175, v175, v254
	v_cmp_lt_f32_e32 vcc, 0x41000000, v175
	s_cbranch_vccnz .Latt_resc_a
.Latt_cont_a:
	v_exp_f32_e32 v112, v112
	v_exp_f32_e32 v113, v113
	v_exp_f32_e32 v114, v114
	v_exp_f32_e32 v115, v115
	v_exp_f32_e32 v116, v116
	v_exp_f32_e32 v117, v117
	v_exp_f32_e32 v118, v118
	v_exp_f32_e32 v119, v119
	v_add_f32_e32 v189, v189, v112
	v_add_f32_e32 v189, v189, v113
	v_add_f32_e32 v189, v189, v114
	v_add_f32_e32 v189, v189, v115
	v_add_f32_e32 v189, v189, v116
	v_add_f32_e32 v189, v189, v117
	v_add_f32_e32 v189, v189, v118
	v_add_f32_e32 v189, v189, v119
	v_cvt_pk_bf16_f32 v112, v112, v113
	v_cvt_pk_bf16_f32 v113, v114, v115
	v_cvt_pk_bf16_f32 v114, v116, v117
	v_cvt_pk_bf16_f32 v115, v118, v119
	v_exp_f32_e32 v120, v120
	v_exp_f32_e32 v121, v121
	s_waitcnt lgkmcnt(8)
	v_mfma_f32_32x32x16_bf16 v[48:63], v[232:235], v[112:115], v[48:63]
	v_exp_f32_e32 v122, v122
	v_exp_f32_e32 v123, v123
	v_exp_f32_e32 v124, v124
	v_mfma_f32_32x32x16_bf16 v[32:47], v[236:239], v[112:115], v[32:47]
	v_exp_f32_e32 v125, v125
	v_exp_f32_e32 v126, v126
	v_exp_f32_e32 v127, v127
	v_mfma_f32_32x32x16_bf16 v[16:31], v[240:243], v[112:115], v[16:31]
	v_add_f32_e32 v189, v189, v120
	v_add_f32_e32 v189, v189, v121
	v_add_f32_e32 v189, v189, v122
	v_add_f32_e32 v189, v189, v123
	v_add_f32_e32 v189, v189, v124
	v_add_f32_e32 v189, v189, v125
	v_mfma_f32_32x32x16_bf16 v[0:15], v[244:247], v[112:115], v[0:15]
	ds_read_b128 v[232:235], v167 offset:32768
	ds_read_b128 v[236:239], v167 offset:36864
	ds_read_b128 v[240:243], v167 offset:40960
	ds_read_b128 v[244:247], v167 offset:45056
	v_add_f32_e32 v189, v189, v126
	v_add_f32_e32 v189, v189, v127
	v_cvt_pk_bf16_f32 v116, v120, v121
	v_cvt_pk_bf16_f32 v117, v122, v123
	v_cvt_pk_bf16_f32 v118, v124, v125
	v_cvt_pk_bf16_f32 v119, v126, v127
	s_nop 0
	s_waitcnt lgkmcnt(8)
	v_mfma_f32_32x32x16_bf16 v[48:63], v[64:67], v[116:119], v[48:63]
	v_exp_f32_e32 v80, v80
	v_exp_f32_e32 v81, v81
	v_exp_f32_e32 v82, v82
	v_mfma_f32_32x32x16_bf16 v[32:47], v[68:71], v[116:119], v[32:47]
	v_exp_f32_e32 v83, v83
	v_exp_f32_e32 v84, v84
	v_exp_f32_e32 v85, v85
	v_mfma_f32_32x32x16_bf16 v[16:31], v[72:75], v[116:119], v[16:31]
	v_exp_f32_e32 v86, v86
	v_exp_f32_e32 v87, v87
	v_add_f32_e32 v189, v189, v80
	v_add_f32_e32 v189, v189, v81
	v_mfma_f32_32x32x16_bf16 v[0:15], v[76:79], v[116:119], v[0:15]
	v_add_f32_e32 v189, v189, v82
	v_add_f32_e32 v189, v189, v83
	v_add_f32_e32 v189, v189, v84
	v_add_f32_e32 v189, v189, v85
	v_add_f32_e32 v189, v189, v86
	v_add_f32_e32 v189, v189, v87
	v_cvt_pk_bf16_f32 v80, v80, v81
	v_cvt_pk_bf16_f32 v81, v82, v83
	v_cvt_pk_bf16_f32 v82, v84, v85
	v_cvt_pk_bf16_f32 v83, v86, v87
	s_nop 0
	s_waitcnt lgkmcnt(4)
	v_mfma_f32_32x32x16_bf16 v[48:63], v[216:219], v[80:83], v[48:63]
	v_exp_f32_e32 v88, v88
	v_exp_f32_e32 v89, v89
	v_exp_f32_e32 v90, v90
	v_mfma_f32_32x32x16_bf16 v[32:47], v[220:223], v[80:83], v[32:47]
	v_exp_f32_e32 v91, v91
	v_exp_f32_e32 v92, v92
	v_exp_f32_e32 v93, v93
	v_mfma_f32_32x32x16_bf16 v[16:31], v[224:227], v[80:83], v[16:31]
	v_exp_f32_e32 v94, v94
	v_exp_f32_e32 v95, v95
	v_add_f32_e32 v189, v189, v88
	v_add_f32_e32 v189, v189, v89
	v_mfma_f32_32x32x16_bf16 v[0:15], v[228:231], v[80:83], v[0:15]
	v_add_f32_e32 v189, v189, v90
	v_add_f32_e32 v189, v189, v91
	v_add_f32_e32 v189, v189, v92
	v_add_f32_e32 v189, v189, v93
	v_add_f32_e32 v189, v189, v94
	v_add_f32_e32 v189, v189, v95
	v_cvt_pk_bf16_f32 v84, v88, v89
	v_cvt_pk_bf16_f32 v85, v90, v91
	v_cvt_pk_bf16_f32 v86, v92, v93
	v_cvt_pk_bf16_f32 v87, v94, v95
	s_nop 0
	s_waitcnt lgkmcnt(0)
	v_mfma_f32_32x32x16_bf16 v[48:63], v[232:235], v[84:87], v[48:63]
	v_mfma_f32_32x32x16_bf16 v[32:47], v[236:239], v[84:87], v[32:47]
	v_mfma_f32_32x32x16_bf16 v[16:31], v[240:243], v[84:87], v[16:31]
	v_mfma_f32_32x32x16_bf16 v[0:15], v[244:247], v[84:87], v[0:15]
	s_waitcnt vmcnt(0)
	s_barrier
	ds_read_b128 v[64:67], v173 offset:0
	ds_read_b128 v[68:71], v173 offset:4096
	ds_read_b128 v[72:75], v171 offset:0
	ds_read_b128 v[76:79], v171 offset:4096
	ds_read_b128 v[216:219], v169 offset:0
	ds_read_b128 v[220:223], v169 offset:4096
	ds_read_b128 v[224:227], v167 offset:0
	ds_read_b128 v[228:231], v167 offset:4096
	ds_read_b128 v[232:235], v173 offset:8192
	ds_read_b128 v[236:239], v173 offset:12288
	ds_read_b128 v[240:243], v173 offset:16384
	ds_read_b128 v[244:247], v173 offset:20480
	s_add_u32 m0, s44, 0x6000
	s_waitcnt lgkmcnt(11)
	v_mfma_f32_32x32x16_bf16 v[112:127], v[64:67], v[140:143], v[96:111]
	ds_read_b128 v[64:67], v171 offset:8192
	global_load_lds_dwordx4 v200, s[40:41]
	s_add_u32 m0, s44, 0x6400
	s_waitcnt lgkmcnt(11)
	v_mfma_f32_32x32x16_bf16 v[80:95], v[68:71], v[140:143], v[96:111]
	ds_read_b128 v[68:71], v171 offset:12288
	global_load_lds_dwordx4 v190, s[40:41]
	s_add_u32 m0, s45, 0x6000
	s_waitcnt lgkmcnt(11)
	v_mfma_f32_32x32x16_bf16 v[112:127], v[72:75], v[136:139], v[112:127]
	ds_read_b128 v[72:75], v171 offset:16384
	global_load_lds_dwordx4 v192, s[42:43]
	s_add_u32 m0, s45, 0x6400
	s_waitcnt lgkmcnt(11)
	v_mfma_f32_32x32x16_bf16 v[80:95], v[76:79], v[136:139], v[80:95]
	ds_read_b128 v[76:79], v171 offset:20480
	global_load_lds_dwordx4 v194, s[42:43]
	s_add_u32 m0, s45, 0x6800
	s_waitcnt lgkmcnt(11)
	v_mfma_f32_32x32x16_bf16 v[112:127], v[216:219], v[132:135], v[112:127]
	ds_read_b128 v[216:219], v169 offset:8192
	global_load_lds_dwordx4 v196, s[42:43]
	s_add_u32 m0, s45, 0x6c00
	s_waitcnt lgkmcnt(11)
	v_mfma_f32_32x32x16_bf16 v[80:95], v[220:223], v[132:135], v[80:95]
	ds_read_b128 v[220:223], v169 offset:12288
	global_load_lds_dwordx4 v198, s[42:43]
	s_waitcnt lgkmcnt(11)
	v_mfma_f32_32x32x16_bf16 v[112:127], v[224:227], v[128:131], v[112:127]
	ds_read_b128 v[224:227], v169 offset:16384
	s_waitcnt lgkmcnt(11)
	v_mfma_f32_32x32x16_bf16 v[80:95], v[228:231], v[128:131], v[80:95]
	ds_read_b128 v[228:231], v169 offset:20480
	s_add_u32 s40, s40, 0x18000
	s_addc_u32 s41, s41, 0
	s_add_u32 s42, s42, 0x80
	s_addc_u32 s43, s43, 0
	s_nop 7
	s_nop 3
	v_max3_f32 v175, v112, v113, v114
	v_max3_f32 v177, v115, v116, v117
	v_max3_f32 v179, v118, v119, v120
	v_max3_f32 v181, v121, v122, v123
	v_max3_f32 v248, v124, v125, v126
	v_max3_f32 v249, v127, v80, v81
	v_max3_f32 v250, v82, v83, v84
	v_max3_f32 v251, v85, v86, v87
	v_max3_f32 v253, v88, v89, v90
	v_max3_f32 v254, v91, v92, v93
	v_max3_f32 v175, v175, v177, v179
	v_max3_f32 v181, v181, v248, v249
	v_max3_f32 v250, v250, v251, v253
	v_max3_f32 v254, v254, v94, v95
	v_max3_f32 v175, v175, v181, v250
	v_max_f32_e32 v175, v175, v254
	v_cmp_lt_f32_e32 vcc, 0x41000000, v175
	s_cbranch_vccnz .Latt_resc_b
